# P2: block-inverse combination stages: all LDS operand reads of each stage issued at its top (no read-wait-mfma chains)
# speedup vs baseline: 1.0089x; 1.0006x over previous
; __device__ void rwkv_prep_item(const Params& p, char* lds_, int item, PrepRaw& raw, int next_item) {
;     ...
;     __syncthreads();
;     if (wave < 2) {
;       const int R = 32 * wave + 16, C = 32 * wave;
;       f32x4 m = {0.f, 0.f, 0.f, 0.f};
; #pragma unroll
;       for (int ks = 0; ks < 4; ++ks)
;         m = __builtin_amdgcn_mfma_f32_16x16x4f32(Tf[(R + r16) * 68 + C + 4 * ks + g4], Tf[(C + 4 * ks + g4) * 68 + C + r16], m, 0, 0, 0);
;       float* mw = Ms + wave * 16 * 17;
; #pragma unroll
;       for (int e = 0; e < 4; ++e) mw[(4 * g4 + e) * 17 + r16] = m[e];
;       f32x4 t = {0.f, 0.f, 0.f, 0.f};
; #pragma unroll
;       for (int ks = 0; ks < 4; ++ks)
;         t = __builtin_amdgcn_mfma_f32_16x16x4f32(Tf[(R + r16) * 68 + R + 4 * ks + g4], mw[(4 * ks + g4) * 17 + r16], t, 0, 0, 0);
; #pragma unroll
;       for (int e = 0; e < 4; ++e) Tf[(R + 4 * g4 + e) * 68 + C + r16] = t[e];
;     }
;     __syncthreads();
;     float* M2 = Ms + 2 * 16 * 17;
;     const int ti = (wave >> 1) & 1, tj = wave & 1;
;     if (wave < 4) {
;       f32x4 m = {0.f, 0.f, 0.f, 0.f};
; #pragma unroll
;       for (int ks = 0; ks < 8; ++ks)
;         m = __builtin_amdgcn_mfma_f32_16x16x4f32(Tf[(32 + 16 * ti + r16) * 68 + 4 * ks + g4], Tf[(4 * ks + g4) * 68 + 16 * tj + r16], m, 0, 0, 0);
; #pragma unroll
;       for (int e = 0; e < 4; ++e) M2[(16 * ti + 4 * g4 + e) * 33 + 16 * tj + r16] = m[e];
;     }
;     __syncthreads();
;     if (wave < 4) {
;       f32x4 t = {0.f, 0.f, 0.f, 0.f};
; #pragma unroll
;       for (int ks = 0; ks < 8; ++ks)
;         t = __builtin_amdgcn_mfma_f32_16x16x4f32(Tf[(32 + 16 * ti + r16) * 68 + 32 + 4 * ks + g4], M2[(4 * ks + g4) * 33 + 16 * tj + r16], t, 0, 0, 0);
; #pragma unroll
;       for (int e = 0; e < 4; ++e) Tf[(32 + 16 * ti + 4 * g4 + e) * 68 + 16 * tj + r16] = t[e];
;     }
;     __syncthreads();
.LBB0_323:
	s_or_b64 exec, exec, s[58:59]
	s_waitcnt lgkmcnt(0)
	s_barrier
	s_and_saveexec_b64 s[58:59], s[10:11]
	s_cbranch_execz .LBB0_325
	ds_read2_b32 v[22:23], v207 offset1:4
	ds_read_b32 v18, v246
	ds_read_b32 v24, v246 offset:1088
	ds_read2_b32 v[48:49], v207 offset0:8 offset1:12
	ds_read_b32 v25, v246 offset:2176
	ds_read_b32 v26, v246 offset:3264
	s_waitcnt lgkmcnt(4)
	v_mfma_f32_16x16x4_f32 v[18:21], v22, v18, 0
	s_waitcnt lgkmcnt(3)
	v_mfma_f32_16x16x4_f32 v[18:21], v23, v24, v[18:21]
	s_waitcnt lgkmcnt(1)
	v_mfma_f32_16x16x4_f32 v[18:21], v48, v25, v[18:21]
	v_add_u32_e32 v22, v208, v209
	s_waitcnt lgkmcnt(0)
	v_mfma_f32_16x16x4_f32 v[18:21], v49, v26, v[18:21]
	s_nop 9
	ds_write2_b32 v22, v18, v19 offset1:17
	ds_write2_b32 v22, v20, v21 offset0:34 offset1:51
	ds_read2_b32 v[22:23], v207 offset0:16 offset1:20
	ds_read2_b32 v[24:25], v247 offset1:68
	ds_read2_b32 v[48:49], v207 offset0:24 offset1:28
	ds_read2_b32 v[50:51], v247 offset0:136 offset1:204
	s_waitcnt lgkmcnt(2)
	v_mfma_f32_16x16x4_f32 v[18:21], v22, v24, 0
	v_mfma_f32_16x16x4_f32 v[18:21], v23, v25, v[18:21]
	s_waitcnt lgkmcnt(0)
	v_mfma_f32_16x16x4_f32 v[18:21], v48, v50, v[18:21]
	v_mfma_f32_16x16x4_f32 v[18:21], v49, v51, v[18:21]
	s_nop 9
	ds_write2_b32 v248, v18, v19 offset1:68
	ds_write2_b32 v248, v20, v21 offset0:136 offset1:204
.LBB0_325:
	s_or_b64 exec, exec, s[58:59]
	v_add_u32_e32 v18, 0x2000, v210
	s_waitcnt lgkmcnt(0)
	s_barrier
	s_and_saveexec_b64 s[58:59], s[12:13]
	s_cbranch_execz .LBB0_327
	v_add_u32_e32 v19, v211, v209
	ds_read2_b32 v[24:25], v18 offset0:128 offset1:132
	ds_read_b32 v20, v19
	ds_read_b32 v26, v19 offset:1088
	ds_read2_b32 v[48:49], v18 offset0:136 offset1:140
	ds_read_b32 v27, v19 offset:2176
	ds_read_b32 v28, v19 offset:3264
	ds_read2_b32 v[50:51], v18 offset0:144 offset1:148
	ds_read_b32 v29, v19 offset:4352
	ds_read_b32 v30, v19 offset:5440
	ds_read2_b32 v[52:53], v18 offset0:152 offset1:156
	ds_read_b32 v31, v19 offset:6528
	ds_read_b32 v19, v19 offset:7616
	s_waitcnt lgkmcnt(10)
	v_mfma_f32_16x16x4_f32 v[20:23], v24, v20, 0
	s_waitcnt lgkmcnt(9)
	v_mfma_f32_16x16x4_f32 v[20:23], v25, v26, v[20:23]
	s_waitcnt lgkmcnt(7)
	v_mfma_f32_16x16x4_f32 v[20:23], v48, v27, v[20:23]
	s_waitcnt lgkmcnt(6)
	v_mfma_f32_16x16x4_f32 v[20:23], v49, v28, v[20:23]
	s_waitcnt lgkmcnt(4)
	v_mfma_f32_16x16x4_f32 v[20:23], v50, v29, v[20:23]
	s_waitcnt lgkmcnt(3)
	v_mfma_f32_16x16x4_f32 v[20:23], v51, v30, v[20:23]
	s_waitcnt lgkmcnt(1)
	v_mfma_f32_16x16x4_f32 v[20:23], v52, v31, v[20:23]
	s_waitcnt lgkmcnt(0)
	v_mfma_f32_16x16x4_f32 v[20:23], v53, v19, v[20:23]
	s_nop 9
	ds_write2_b32 v249, v20, v21 offset1:33
	ds_write2_b32 v249, v22, v23 offset0:66 offset1:99
.LBB0_327:
	s_or_b64 exec, exec, s[58:59]
	s_waitcnt lgkmcnt(0)
	s_barrier
	s_and_saveexec_b64 s[58:59], s[12:13]
	s_cbranch_execz .LBB0_276
	ds_read2_b32 v[24:25], v18 offset0:160 offset1:164
	ds_read2_b32 v[26:27], v250 offset1:132
	v_add_u32_e32 v19, 0x400, v250
	ds_read2_b32 v[48:49], v18 offset0:168 offset1:172
	ds_read2_b32 v[50:51], v19 offset0:8 offset1:140
	v_add_u32_e32 v19, 0x800, v250
	ds_read2_b32 v[52:53], v18 offset0:176 offset1:180
	ds_read2_b32 v[54:55], v19 offset0:16 offset1:148
	ds_read2_b32 v[56:57], v18 offset0:184 offset1:188
	v_add_u32_e32 v18, 0xc00, v250
	ds_read2_b32 v[58:59], v18 offset0:24 offset1:156
	v_add_u32_e32 v60, 0x2000, v212
	v_add_u32_e32 v61, 0x2400, v212
	s_waitcnt lgkmcnt(6)
	v_mfma_f32_16x16x4_f32 v[20:23], v24, v26, 0
	v_mfma_f32_16x16x4_f32 v[20:23], v25, v27, v[20:23]
	s_waitcnt lgkmcnt(4)
	v_mfma_f32_16x16x4_f32 v[20:23], v48, v50, v[20:23]
	v_mfma_f32_16x16x4_f32 v[20:23], v49, v51, v[20:23]
	s_waitcnt lgkmcnt(2)
	v_mfma_f32_16x16x4_f32 v[20:23], v52, v54, v[20:23]
	v_mfma_f32_16x16x4_f32 v[20:23], v53, v55, v[20:23]
	s_waitcnt lgkmcnt(0)
	v_mfma_f32_16x16x4_f32 v[18:21], v56, v58, v[20:23]
	v_mfma_f32_16x16x4_f32 v[18:21], v57, v59, v[18:21]
	s_nop 9
	ds_write2_b32 v60, v18, v19 offset0:128 offset1:196
	ds_write2_b32 v61, v20, v21 offset0:8 offset1:76
	s_branch .LBB0_276
